# rows phase prologue: gains, modulation rows and dt weights staged to LDS with batched loads (2 round trips instead of 48 serialized)
# speedup vs baseline: 1.0779x; 1.0192x over previous
.LBB0_400:
	s_nop 0
	v_readlane_b32 s0, v255, 23
	v_readlane_b32 s1, v255, 24
	s_and_b64 vcc, exec, s[0:1]
	s_cbranch_vccz .LBB0_512
	v_readlane_b32 s0, v255, 21
	v_readlane_b32 s1, v255, 22
	s_andn2_b64 vcc, exec, s[0:1]
	s_cbranch_vccnz .LBB0_511
	s_waitcnt vmcnt(0)
	v_mov_b32_e32 v34, v203
	s_movk_i32 s0, 0x2000
	s_nop 0
	v_cmp_gt_i32_e32 vcc, s0, v34
	v_readlane_b32 s0, v254, 27
	v_readfirstlane_b32 s2, v34
	v_readlane_b32 s1, v254, 28
	v_and_b32_e32 v38, 7, v34
	s_and_b64 s[4:5], s[0:1], vcc
	s_mov_b64 s[0:1], exec
	v_readlane_b32 s36, v253, 32
	v_readlane_b32 s37, v253, 33
	v_readlane_b32 s24, v254, 2
	v_readlane_b32 s38, v253, 34
	v_readlane_b32 s39, v253, 35
	v_readlane_b32 s36, v254, 29
	s_and_b64 s[4:5], s[0:1], s[4:5]
	v_readlane_b32 s25, v254, 3
	s_movk_i32 s3, 0x1ff
	s_movk_i32 s26, 0x4020
	s_movk_i32 s28, 0xc00
	s_movk_i32 s29, 0x21ff
	v_readlane_b32 s48, v253, 44
	v_readlane_b32 s49, v253, 45
	v_readlane_b32 s50, v253, 46
	v_readlane_b32 s51, v253, 47
	v_readlane_b32 s37, v254, 30
	v_readlane_b32 s38, v254, 31
	v_readlane_b32 s39, v254, 32
	v_readlane_b32 s40, v253, 36
	v_readlane_b32 s41, v253, 37
	v_readlane_b32 s42, v253, 38
	v_readlane_b32 s43, v253, 39
	v_readlane_b32 s44, v253, 40
	v_readlane_b32 s45, v253, 41
	v_readlane_b32 s46, v253, 42
	v_readlane_b32 s47, v253, 43
	v_lshlrev_b32_e32 v0, 2, v34
	v_add_u32_e32 v1, 0xa000, v0
	v_add_u32_e32 v2, 0x13000, v0
	v_add_u32_e32 v3, 0x1c000, v0
	v_add_u32_e32 v4, 0x8000, v0
	v_lshrrev_b32_e32 v8, 3, v34
	v_lshlrev_b32_e32 v5, 12, v38
	v_lshl_add_u32 v5, v8, 2, v5
	s_movk_i32 s34, 0x4020
	v_mul_lo_u32 v6, v8, s34
	v_lshl_add_u32 v6, v38, 2, v6
	v_mov_b32_e32 v7, 0
	v_readlane_b32 s40, v255, 15
	v_readlane_b32 s41, v255, 20
	v_readlane_b32 s42, v254, 31
	v_readlane_b32 s43, v254, 32
	v_readlane_b32 s44, v253, 46
	v_readlane_b32 s45, v253, 47
	v_readlane_b32 s46, v253, 44
	v_readlane_b32 s47, v253, 45
	v_readlane_b32 s48, v253, 48
	v_readlane_b32 s49, v253, 49
	v_readlane_b32 s50, v255, 16
	v_readlane_b32 s6, v254, 27
	v_readlane_b32 s7, v254, 28
	s_mul_i32 s54, s40, 0x3000
	s_add_u32 s54, s54, 0x2000
	s_add_u32 s52, s24, s54
	s_addc_u32 s53, s25, 0
	global_load_dword v62, v0, s[52:53]
	global_load_dword v63, v0, s[52:53] offset:2048
	s_add_u32 s52, s52, 0x3000
	s_addc_u32 s53, s53, 0
	global_load_dword v64, v0, s[52:53]
	global_load_dword v65, v0, s[52:53] offset:2048
	s_add_u32 s52, s52, 0x3000
	s_addc_u32 s53, s53, 0
	global_load_dword v66, v0, s[52:53]
	global_load_dword v67, v0, s[52:53] offset:2048
	s_add_u32 s52, s52, 0x3000
	s_addc_u32 s53, s53, 0
	global_load_dword v68, v0, s[52:53]
	global_load_dword v69, v0, s[52:53] offset:2048
	s_add_u32 s52, s52, 0x3000
	s_addc_u32 s53, s53, 0
	global_load_dword v70, v0, s[52:53]
	global_load_dword v71, v0, s[52:53] offset:2048
	s_add_u32 s52, s52, 0x3000
	s_addc_u32 s53, s53, 0
	global_load_dword v72, v0, s[52:53]
	global_load_dword v73, v0, s[52:53] offset:2048
	s_add_u32 s52, s52, 0x3000
	s_addc_u32 s53, s53, 0
	global_load_dword v74, v0, s[52:53]
	global_load_dword v75, v0, s[52:53] offset:2048
	s_add_u32 s52, s52, 0x3000
	s_addc_u32 s53, s53, 0
	global_load_dword v76, v0, s[52:53]
	global_load_dword v77, v0, s[52:53] offset:2048
	s_add_u32 s52, s52, 0x3000
	s_addc_u32 s53, s53, 0
	global_load_dword v78, v0, s[52:53]
	global_load_dword v79, v0, s[52:53] offset:2048
	s_lshl_b32 s54, s42, 2
	s_add_u32 s52, s44, s54
	s_addc_u32 s53, s45, 0
	global_load_dword v80, v0, s[52:53]
	global_load_dword v81, v0, s[52:53] offset:2048
	s_and_b64 vcc, exec, s[6:7]
	s_cbranch_vccz .Lrp_nolnorm
	s_lshl_b32 s54, s43, 2
	s_add_u32 s52, s46, s54
	s_addc_u32 s53, s47, 0
	global_load_dword v82, v0, s[52:53]
	global_load_dword v83, v0, s[52:53] offset:2048
	s_mul_i32 s54, s50, 0x4020
	s_add_u32 s54, s54, 0x4000
	s_add_u32 s52, s48, s54
	s_addc_u32 s53, s49, 0
	global_load_dword v84, v6, s[52:53]
	s_add_u32 s52, s52, 0x100800
	s_addc_u32 s53, s53, 0
	global_load_dword v85, v6, s[52:53]
	s_add_u32 s52, s52, 0x100800
	s_addc_u32 s53, s53, 0
	global_load_dword v86, v6, s[52:53]
	s_add_u32 s52, s52, 0x100800
	s_addc_u32 s53, s53, 0
	global_load_dword v87, v6, s[52:53]
	s_add_u32 s52, s52, 0x100800
	s_addc_u32 s53, s53, 0
	global_load_dword v88, v6, s[52:53]
	s_add_u32 s52, s52, 0x100800
	s_addc_u32 s53, s53, 0
	global_load_dword v89, v6, s[52:53]
	s_add_u32 s52, s52, 0x100800
	s_addc_u32 s53, s53, 0
	global_load_dword v90, v6, s[52:53]
	s_add_u32 s52, s52, 0x100800
	s_addc_u32 s53, s53, 0
	global_load_dword v91, v6, s[52:53]
	s_add_u32 s52, s52, 0x100800
	s_addc_u32 s53, s53, 0
	global_load_dword v92, v6, s[52:53]
	s_add_u32 s52, s52, 0x100800
	s_addc_u32 s53, s53, 0
	global_load_dword v93, v6, s[52:53]
	s_add_u32 s52, s52, 0x100800
	s_addc_u32 s53, s53, 0
	global_load_dword v94, v6, s[52:53]
	s_add_u32 s52, s52, 0x100800
	s_addc_u32 s53, s53, 0
	global_load_dword v95, v6, s[52:53]
	s_add_u32 s52, s52, 0x100800
	s_addc_u32 s53, s53, 0
	global_load_dword v96, v6, s[52:53]
	s_add_u32 s52, s52, 0x100800
	s_addc_u32 s53, s53, 0
	global_load_dword v97, v6, s[52:53]
	s_add_u32 s52, s52, 0x100800
	s_addc_u32 s53, s53, 0
	global_load_dword v98, v6, s[52:53]
	s_add_u32 s52, s52, 0x100800
	s_addc_u32 s53, s53, 0
	global_load_dword v99, v6, s[52:53]
	s_waitcnt vmcnt(0)
	ds_write_b32 v1, v62
	ds_write_b32 v1, v63 offset:2048
	ds_write_b32 v1, v64 offset:4096
	ds_write_b32 v1, v65 offset:6144
	ds_write_b32 v1, v66 offset:8192
	ds_write_b32 v1, v67 offset:10240
	ds_write_b32 v1, v68 offset:12288
	ds_write_b32 v1, v69 offset:14336
	ds_write_b32 v1, v70 offset:16384
	ds_write_b32 v1, v71 offset:18432
	ds_write_b32 v1, v72 offset:20480
	ds_write_b32 v1, v73 offset:22528
	ds_write_b32 v1, v74 offset:24576
	ds_write_b32 v1, v75 offset:26624
	ds_write_b32 v1, v76 offset:28672
	ds_write_b32 v1, v77 offset:30720
	ds_write_b32 v1, v78 offset:32768
	ds_write_b32 v1, v79 offset:34816
	ds_write_b32 v4, v80
	ds_write_b32 v4, v81 offset:2048
	ds_write_b32 v4, v82 offset:4096
	ds_write_b32 v4, v83 offset:6144
	ds_write_b32 v5, v84
	ds_write_b32 v5, v85 offset:256
	ds_write_b32 v5, v86 offset:512
	ds_write_b32 v5, v87 offset:768
	ds_write_b32 v5, v88 offset:1024
	ds_write_b32 v5, v89 offset:1280
	ds_write_b32 v5, v90 offset:1536
	ds_write_b32 v5, v91 offset:1792
	ds_write_b32 v5, v92 offset:2048
	ds_write_b32 v5, v93 offset:2304
	ds_write_b32 v5, v94 offset:2560
	ds_write_b32 v5, v95 offset:2816
	ds_write_b32 v5, v96 offset:3072
	ds_write_b32 v5, v97 offset:3328
	ds_write_b32 v5, v98 offset:3584
	ds_write_b32 v5, v99 offset:3840
	s_mul_i32 s54, s41, 0x3000
	s_add_u32 s52, s24, s54
	s_addc_u32 s53, s25, 0
	s_add_u32 s56, s52, 0x1000
	s_addc_u32 s57, s53, 0
	global_load_dword v165, v0, s[52:53]
	global_load_dword v166, v0, s[52:53] offset:2048
	global_load_dword v100, v0, s[56:57]
	global_load_dword v101, v0, s[56:57] offset:2048
	s_add_u32 s52, s52, 0x3000
	s_addc_u32 s53, s53, 0
	s_add_u32 s56, s56, 0x3000
	s_addc_u32 s57, s57, 0
	global_load_dword v167, v0, s[52:53]
	global_load_dword v168, v0, s[52:53] offset:2048
	global_load_dword v102, v0, s[56:57]
	global_load_dword v103, v0, s[56:57] offset:2048
	s_add_u32 s52, s52, 0x3000
	s_addc_u32 s53, s53, 0
	s_add_u32 s56, s56, 0x3000
	s_addc_u32 s57, s57, 0
	global_load_dword v169, v0, s[52:53]
	global_load_dword v170, v0, s[52:53] offset:2048
	global_load_dword v104, v0, s[56:57]
	global_load_dword v105, v0, s[56:57] offset:2048
	s_add_u32 s52, s52, 0x3000
	s_addc_u32 s53, s53, 0
	s_add_u32 s56, s56, 0x3000
	s_addc_u32 s57, s57, 0
	global_load_dword v171, v0, s[52:53]
	global_load_dword v172, v0, s[52:53] offset:2048
	global_load_dword v106, v0, s[56:57]
	global_load_dword v107, v0, s[56:57] offset:2048
	s_add_u32 s52, s52, 0x3000
	s_addc_u32 s53, s53, 0
	s_add_u32 s56, s56, 0x3000
	s_addc_u32 s57, s57, 0
	global_load_dword v173, v0, s[52:53]
	global_load_dword v174, v0, s[52:53] offset:2048
	global_load_dword v108, v0, s[56:57]
	global_load_dword v109, v0, s[56:57] offset:2048
	s_add_u32 s52, s52, 0x3000
	s_addc_u32 s53, s53, 0
	s_add_u32 s56, s56, 0x3000
	s_addc_u32 s57, s57, 0
	global_load_dword v175, v0, s[52:53]
	global_load_dword v176, v0, s[52:53] offset:2048
	global_load_dword v110, v0, s[56:57]
	global_load_dword v111, v0, s[56:57] offset:2048
	s_add_u32 s52, s52, 0x3000
	s_addc_u32 s53, s53, 0
	s_add_u32 s56, s56, 0x3000
	s_addc_u32 s57, s57, 0
	global_load_dword v177, v0, s[52:53]
	global_load_dword v178, v0, s[52:53] offset:2048
	global_load_dword v112, v0, s[56:57]
	global_load_dword v113, v0, s[56:57] offset:2048
	s_add_u32 s52, s52, 0x3000
	s_addc_u32 s53, s53, 0
	s_add_u32 s56, s56, 0x3000
	s_addc_u32 s57, s57, 0
	global_load_dword v179, v0, s[52:53]
	global_load_dword v180, v0, s[52:53] offset:2048
	global_load_dword v114, v0, s[56:57]
	global_load_dword v115, v0, s[56:57] offset:2048
	s_add_u32 s52, s52, 0x3000
	s_addc_u32 s53, s53, 0
	s_add_u32 s56, s56, 0x3000
	s_addc_u32 s57, s57, 0
	global_load_dword v181, v0, s[52:53]
	global_load_dword v182, v0, s[52:53] offset:2048
	global_load_dword v116, v0, s[56:57]
	global_load_dword v117, v0, s[56:57] offset:2048
	s_waitcnt vmcnt(0)
	ds_write_b32 v2, v165
	ds_write_b32 v2, v166 offset:2048
	ds_write_b32 v2, v167 offset:4096
	ds_write_b32 v2, v168 offset:6144
	ds_write_b32 v2, v169 offset:8192
	ds_write_b32 v2, v170 offset:10240
	ds_write_b32 v2, v171 offset:12288
	ds_write_b32 v2, v172 offset:14336
	ds_write_b32 v2, v173 offset:16384
	ds_write_b32 v2, v174 offset:18432
	ds_write_b32 v2, v175 offset:20480
	ds_write_b32 v2, v176 offset:22528
	ds_write_b32 v2, v177 offset:24576
	ds_write_b32 v2, v178 offset:26624
	ds_write_b32 v2, v179 offset:28672
	ds_write_b32 v2, v180 offset:30720
	ds_write_b32 v2, v181 offset:32768
	ds_write_b32 v2, v182 offset:34816
	ds_write_b32 v3, v100
	ds_write_b32 v3, v101 offset:2048
	ds_write_b32 v3, v102 offset:4096
	ds_write_b32 v3, v103 offset:6144
	ds_write_b32 v3, v104 offset:8192
	ds_write_b32 v3, v105 offset:10240
	ds_write_b32 v3, v106 offset:12288
	ds_write_b32 v3, v107 offset:14336
	ds_write_b32 v3, v108 offset:16384
	ds_write_b32 v3, v109 offset:18432
	ds_write_b32 v3, v110 offset:20480
	ds_write_b32 v3, v111 offset:22528
	ds_write_b32 v3, v112 offset:24576
	ds_write_b32 v3, v113 offset:26624
	ds_write_b32 v3, v114 offset:28672
	ds_write_b32 v3, v115 offset:30720
	ds_write_b32 v3, v116 offset:32768
	ds_write_b32 v3, v117 offset:34816
	s_branch .Lrp_done
.Lrp_nolnorm:
	s_waitcnt vmcnt(0)
	ds_write_b32 v1, v62
	ds_write_b32 v1, v63 offset:2048
	ds_write_b32 v1, v64 offset:4096
	ds_write_b32 v1, v65 offset:6144
	ds_write_b32 v1, v66 offset:8192
	ds_write_b32 v1, v67 offset:10240
	ds_write_b32 v1, v68 offset:12288
	ds_write_b32 v1, v69 offset:14336
	ds_write_b32 v1, v70 offset:16384
	ds_write_b32 v1, v71 offset:18432
	ds_write_b32 v1, v72 offset:20480
	ds_write_b32 v1, v73 offset:22528
	ds_write_b32 v1, v74 offset:24576
	ds_write_b32 v1, v75 offset:26624
	ds_write_b32 v1, v76 offset:28672
	ds_write_b32 v1, v77 offset:30720
	ds_write_b32 v1, v78 offset:32768
	ds_write_b32 v1, v79 offset:34816
	ds_write_b32 v4, v80
	ds_write_b32 v4, v81 offset:2048
	ds_write_b32 v4, v7 offset:4096
	ds_write_b32 v4, v7 offset:6144
	ds_write_b32 v2, v7
	ds_write_b32 v2, v7 offset:2048
	ds_write_b32 v2, v7 offset:4096
	ds_write_b32 v2, v7 offset:6144
	ds_write_b32 v2, v7 offset:8192
	ds_write_b32 v2, v7 offset:10240
	ds_write_b32 v2, v7 offset:12288
	ds_write_b32 v2, v7 offset:14336
	ds_write_b32 v2, v7 offset:16384
	ds_write_b32 v2, v7 offset:18432
	ds_write_b32 v2, v7 offset:20480
	ds_write_b32 v2, v7 offset:22528
	ds_write_b32 v2, v7 offset:24576
	ds_write_b32 v2, v7 offset:26624
	ds_write_b32 v2, v7 offset:28672
	ds_write_b32 v2, v7 offset:30720
	ds_write_b32 v2, v7 offset:32768
	ds_write_b32 v2, v7 offset:34816
	ds_write_b32 v3, v7
	ds_write_b32 v3, v7 offset:2048
	ds_write_b32 v3, v7 offset:4096
	ds_write_b32 v3, v7 offset:6144
	ds_write_b32 v3, v7 offset:8192
	ds_write_b32 v3, v7 offset:10240
	ds_write_b32 v3, v7 offset:12288
	ds_write_b32 v3, v7 offset:14336
	ds_write_b32 v3, v7 offset:16384
	ds_write_b32 v3, v7 offset:18432
	ds_write_b32 v3, v7 offset:20480
	ds_write_b32 v3, v7 offset:22528
	ds_write_b32 v3, v7 offset:24576
	ds_write_b32 v3, v7 offset:26624
	ds_write_b32 v3, v7 offset:28672
	ds_write_b32 v3, v7 offset:30720
	ds_write_b32 v3, v7 offset:32768
	ds_write_b32 v3, v7 offset:34816
.Lrp_done:
	v_readlane_b32 s26, v254, 18
